# static priority: leading half-workgroup (waves 0-3) at s_setprio 1 for each GEMM K-loop, all per-segment flips deleted (on s8p)
# speedup vs baseline: 1.0015x; 1.0015x over previous
.LBB0_321:
	s_ashr_i32 s39, s38, 31
	s_lshl_b64 s[44:45], s[38:39], 19
	s_add_u32 s56, s22, s44
	s_addc_u32 s57, s23, s45
	s_and_b64 s[0:1], s[0:1], exec
	s_cselect_b32 s31, s57, s71
	s_cselect_b32 s39, s56, s70
	s_add_u32 s0, s70, 0x40080
	s_addc_u32 s1, s71, 0
	s_add_u32 s91, s68, 0x100
	v_mov_b32_e32 v2, 0
	s_addc_u32 s92, s69, 0
	s_mov_b32 s93, -2
	v_mov_b32_e32 v3, v2
	v_mov_b32_e32 v4, v2
	v_mov_b32_e32 v5, v2
	v_mov_b32_e32 v6, v2
	v_mov_b32_e32 v7, v2
	v_mov_b32_e32 v8, v2
	v_mov_b32_e32 v9, v2
	v_mov_b32_e32 v10, v2
	v_mov_b32_e32 v11, v2
	v_mov_b32_e32 v12, v2
	v_mov_b32_e32 v13, v2
	v_mov_b32_e32 v18, v2
	v_mov_b32_e32 v19, v2
	v_mov_b32_e32 v20, v2
	v_mov_b32_e32 v21, v2
	v_mov_b32_e32 v26, v2
	v_mov_b32_e32 v27, v2
	v_mov_b32_e32 v28, v2
	v_mov_b32_e32 v29, v2
	v_mov_b32_e32 v34, v2
	v_mov_b32_e32 v35, v2
	v_mov_b32_e32 v36, v2
	v_mov_b32_e32 v37, v2
	v_mov_b32_e32 v42, v2
	v_mov_b32_e32 v43, v2
	v_mov_b32_e32 v44, v2
	v_mov_b32_e32 v45, v2
	v_mov_b32_e32 v50, v2
	v_mov_b32_e32 v51, v2
	v_mov_b32_e32 v52, v2
	v_mov_b32_e32 v53, v2
	v_mov_b32_e32 v14, v2
	s_waitcnt lgkmcnt(0)
	v_mov_b32_e32 v15, v2
	v_mov_b32_e32 v16, v2
	v_mov_b32_e32 v17, v2
	v_mov_b32_e32 v22, v2
	v_mov_b32_e32 v23, v2
	v_mov_b32_e32 v24, v2
	v_mov_b32_e32 v25, v2
	v_mov_b32_e32 v30, v2
	v_mov_b32_e32 v31, v2
	v_mov_b32_e32 v32, v2
	v_mov_b32_e32 v33, v2
	v_mov_b32_e32 v38, v2
	v_mov_b32_e32 v39, v2
	v_mov_b32_e32 v40, v2
	v_mov_b32_e32 v41, v2
	v_mov_b32_e32 v46, v2
	v_mov_b32_e32 v47, v2
	v_mov_b32_e32 v48, v2
	v_mov_b32_e32 v49, v2
	v_mov_b32_e32 v54, v2
	v_mov_b32_e32 v55, v2
	v_mov_b32_e32 v56, v2
	v_mov_b32_e32 v57, v2
	v_mov_b32_e32 v58, v2
	v_mov_b32_e32 v59, v2
	v_mov_b32_e32 v60, v2
	v_mov_b32_e32 v61, v2
	v_mov_b32_e32 v62, v2
	v_mov_b32_e32 v63, v2
	v_mov_b32_e32 v64, v2
	v_mov_b32_e32 v65, v2
	v_mov_b32_e32 v66, v2
	v_mov_b32_e32 v67, v2
	v_mov_b32_e32 v68, v2
	v_mov_b32_e32 v69, v2
	v_mov_b32_e32 v70, v2
	v_mov_b32_e32 v71, v2
	v_mov_b32_e32 v72, v2
	v_mov_b32_e32 v73, v2
	v_mov_b32_e32 v74, v2
	v_mov_b32_e32 v75, v2
	v_mov_b32_e32 v76, v2
	v_mov_b32_e32 v77, v2
	v_mov_b32_e32 v82, v2
	v_mov_b32_e32 v83, v2
	v_mov_b32_e32 v84, v2
	v_mov_b32_e32 v85, v2
	v_mov_b32_e32 v90, v2
	v_mov_b32_e32 v91, v2
	v_mov_b32_e32 v92, v2
	v_mov_b32_e32 v93, v2
	v_mov_b32_e32 v100, v2
	v_mov_b32_e32 v101, v2
	v_mov_b32_e32 v102, v2
	v_mov_b32_e32 v103, v2
	v_mov_b32_e32 v108, v2
	v_mov_b32_e32 v109, v2
	v_mov_b32_e32 v110, v2
	v_mov_b32_e32 v111, v2
	v_mov_b32_e32 v116, v2
	v_mov_b32_e32 v117, v2
	v_mov_b32_e32 v118, v2
	v_mov_b32_e32 v119, v2
	v_mov_b32_e32 v78, v2
	v_mov_b32_e32 v79, v2
	v_mov_b32_e32 v80, v2
	v_mov_b32_e32 v81, v2
	v_mov_b32_e32 v86, v2
	v_mov_b32_e32 v87, v2
	v_mov_b32_e32 v88, v2
	v_mov_b32_e32 v89, v2
	v_mov_b32_e32 v94, v2
	v_mov_b32_e32 v95, v2
	v_mov_b32_e32 v96, v2
	v_mov_b32_e32 v97, v2
	v_mov_b32_e32 v104, v2
	v_mov_b32_e32 v105, v2
	v_mov_b32_e32 v106, v2
	v_mov_b32_e32 v107, v2
	v_mov_b32_e32 v112, v2
	v_mov_b32_e32 v113, v2
	v_mov_b32_e32 v114, v2
	v_mov_b32_e32 v115, v2
	v_mov_b32_e32 v120, v2
	v_mov_b32_e32 v121, v2
	v_mov_b32_e32 v122, v2
	v_mov_b32_e32 v123, v2
	v_mov_b32_e32 v124, v2
	v_mov_b32_e32 v125, v2
	v_mov_b32_e32 v126, v2
	v_mov_b32_e32 v127, v2
	v_mov_b32_e32 v128, v2
	v_mov_b32_e32 v129, v2
	v_mov_b32_e32 v130, v2
	v_mov_b32_e32 v131, v2
	s_bitcmp0_b32 s77, 12
	s_cbranch_scc0 .Lmy_sp_g1
	s_setprio 1

.LBB0_863:
	s_ashr_i32 s57, s56, 31
	s_lshl_b64 s[0:1], s[56:57], 19
	v_readlane_b32 s4, v254, 23
	s_add_u32 s0, s4, s0
	v_readlane_b32 s4, v254, 24
	s_addc_u32 s1, s4, s1
	s_and_b64 s[4:5], s[40:41], exec
	s_cselect_b32 s57, s1, s69
	s_cselect_b32 s95, s0, s68
	s_ashr_i32 s31, s30, 31
	s_lshl_b64 s[4:5], s[30:31], 19
	s_add_u32 s20, s27, s4
	s_addc_u32 s21, s77, s5
	s_and_b64 s[4:5], s[40:41], exec
	s_cselect_b32 s31, s21, s71
	s_cselect_b32 vcc_lo, s20, s70
	s_add_u32 s68, s68, 0x40080
	s_addc_u32 s69, s69, 0
	s_add_u32 vcc_hi, s70, 0x100
	v_mov_b32_e32 v2, 0
	s_addc_u32 s96, s71, 0
	s_mov_b32 s97, -2
	v_mov_b32_e32 v3, v2
	v_mov_b32_e32 v4, v2
	v_mov_b32_e32 v5, v2
	v_mov_b32_e32 v6, v2
	v_mov_b32_e32 v7, v2
	v_mov_b32_e32 v8, v2
	v_mov_b32_e32 v9, v2
	v_mov_b32_e32 v18, v2
	v_mov_b32_e32 v19, v2
	v_mov_b32_e32 v20, v2
	v_mov_b32_e32 v21, v2
	v_mov_b32_e32 v22, v2
	v_mov_b32_e32 v23, v2
	v_mov_b32_e32 v24, v2
	v_mov_b32_e32 v25, v2
	v_mov_b32_e32 v34, v2
	v_mov_b32_e32 v35, v2
	v_mov_b32_e32 v36, v2
	v_mov_b32_e32 v37, v2
	v_mov_b32_e32 v38, v2
	v_mov_b32_e32 v39, v2
	v_mov_b32_e32 v40, v2
	v_mov_b32_e32 v41, v2
	v_mov_b32_e32 v50, v2
	v_mov_b32_e32 v51, v2
	v_mov_b32_e32 v52, v2
	v_mov_b32_e32 v53, v2
	v_mov_b32_e32 v54, v2
	v_mov_b32_e32 v55, v2
	v_mov_b32_e32 v56, v2
	v_mov_b32_e32 v57, v2
	v_mov_b32_e32 v10, v2
	v_mov_b32_e32 v11, v2
	v_mov_b32_e32 v12, v2
	v_mov_b32_e32 v13, v2
	v_mov_b32_e32 v14, v2
	s_waitcnt lgkmcnt(0)
	v_mov_b32_e32 v15, v2
	v_mov_b32_e32 v16, v2
	v_mov_b32_e32 v17, v2
	v_mov_b32_e32 v26, v2
	v_mov_b32_e32 v27, v2
	v_mov_b32_e32 v28, v2
	v_mov_b32_e32 v29, v2
	v_mov_b32_e32 v30, v2
	v_mov_b32_e32 v31, v2
	v_mov_b32_e32 v32, v2
	v_mov_b32_e32 v33, v2
	v_mov_b32_e32 v42, v2
	v_mov_b32_e32 v43, v2
	v_mov_b32_e32 v44, v2
	v_mov_b32_e32 v45, v2
	v_mov_b32_e32 v46, v2
	v_mov_b32_e32 v47, v2
	v_mov_b32_e32 v48, v2
	v_mov_b32_e32 v49, v2
	v_mov_b32_e32 v58, v2
	v_mov_b32_e32 v59, v2
	v_mov_b32_e32 v60, v2
	v_mov_b32_e32 v61, v2
	v_mov_b32_e32 v62, v2
	v_mov_b32_e32 v63, v2
	v_mov_b32_e32 v64, v2
	v_mov_b32_e32 v65, v2
	v_mov_b32_e32 v66, v2
	v_mov_b32_e32 v67, v2
	v_mov_b32_e32 v68, v2
	v_mov_b32_e32 v69, v2
	v_mov_b32_e32 v70, v2
	v_mov_b32_e32 v71, v2
	v_mov_b32_e32 v72, v2
	v_mov_b32_e32 v73, v2
	v_mov_b32_e32 v82, v2
	v_mov_b32_e32 v83, v2
	v_mov_b32_e32 v84, v2
	v_mov_b32_e32 v85, v2
	v_mov_b32_e32 v86, v2
	v_mov_b32_e32 v87, v2
	v_mov_b32_e32 v88, v2
	v_mov_b32_e32 v89, v2
	v_mov_b32_e32 v132, v2
	v_mov_b32_e32 v133, v2
	v_mov_b32_e32 v134, v2
	v_mov_b32_e32 v135, v2
	v_mov_b32_e32 v136, v2
	v_mov_b32_e32 v137, v2
	v_mov_b32_e32 v138, v2
	v_mov_b32_e32 v139, v2
	v_mov_b32_e32 v148, v2
	v_mov_b32_e32 v149, v2
	v_mov_b32_e32 v150, v2
	v_mov_b32_e32 v151, v2
	v_mov_b32_e32 v152, v2
	v_mov_b32_e32 v153, v2
	v_mov_b32_e32 v154, v2
	v_mov_b32_e32 v155, v2
	v_mov_b32_e32 v74, v2
	v_mov_b32_e32 v75, v2
	v_mov_b32_e32 v76, v2
	v_mov_b32_e32 v77, v2
	v_mov_b32_e32 v78, v2
	v_mov_b32_e32 v79, v2
	v_mov_b32_e32 v80, v2
	v_mov_b32_e32 v81, v2
	v_mov_b32_e32 v116, v2
	v_mov_b32_e32 v117, v2
	v_mov_b32_e32 v118, v2
	v_mov_b32_e32 v119, v2
	v_mov_b32_e32 v124, v2
	v_mov_b32_e32 v125, v2
	v_mov_b32_e32 v126, v2
	v_mov_b32_e32 v127, v2
	v_mov_b32_e32 v140, v2
	v_mov_b32_e32 v141, v2
	v_mov_b32_e32 v142, v2
	v_mov_b32_e32 v143, v2
	v_mov_b32_e32 v144, v2
	v_mov_b32_e32 v145, v2
	v_mov_b32_e32 v146, v2
	v_mov_b32_e32 v147, v2
	v_mov_b32_e32 v156, v2
	v_mov_b32_e32 v157, v2
	v_mov_b32_e32 v158, v2
	v_mov_b32_e32 v159, v2
	v_mov_b32_e32 v160, v2
	v_mov_b32_e32 v161, v2
	v_mov_b32_e32 v162, v2
	v_mov_b32_e32 v163, v2
	s_bitcmp0_b32 s91, 12
	s_cbranch_scc0 .Lmy_sp_g2a
	s_setprio 1

.LBB0_907:
	s_ashr_i32 s21, s20, 31
	s_lshl_b64 s[30:31], s[20:21], 19
	v_readlane_b32 s2, v254, 23
	s_add_u32 s30, s2, s30
	v_readlane_b32 s2, v254, 24
	s_addc_u32 s31, s2, s31
	s_and_b64 s[40:41], s[38:39], exec
	s_cselect_b32 s21, s31, s57
	s_cselect_b32 s93, s30, s56
	s_ashr_i32 s53, s52, 31
	s_lshl_b64 s[40:41], s[52:53], 19
	s_add_u32 s40, s27, s40
	s_addc_u32 s41, s77, s41
	s_and_b64 s[44:45], s[38:39], exec
	s_cselect_b32 s15, s41, s69
	s_cselect_b32 s94, s40, s68
	s_add_u32 s56, s56, 0x40080
	s_addc_u32 s57, s57, 0
	s_add_u32 s95, s68, 0x100
	v_mov_b32_e32 v2, 0
	s_addc_u32 vcc_lo, s69, 0
	s_mov_b32 s96, -2
	v_mov_b32_e32 v3, v2
	v_mov_b32_e32 v4, v2
	v_mov_b32_e32 v5, v2
	v_mov_b32_e32 v6, v2
	v_mov_b32_e32 v7, v2
	v_mov_b32_e32 v8, v2
	v_mov_b32_e32 v9, v2
	v_mov_b32_e32 v18, v2
	v_mov_b32_e32 v19, v2
	v_mov_b32_e32 v20, v2
	v_mov_b32_e32 v21, v2
	v_mov_b32_e32 v22, v2
	v_mov_b32_e32 v23, v2
	v_mov_b32_e32 v24, v2
	v_mov_b32_e32 v25, v2
	v_mov_b32_e32 v34, v2
	v_mov_b32_e32 v35, v2
	v_mov_b32_e32 v36, v2
	v_mov_b32_e32 v37, v2
	v_mov_b32_e32 v38, v2
	v_mov_b32_e32 v39, v2
	v_mov_b32_e32 v40, v2
	v_mov_b32_e32 v41, v2
	v_mov_b32_e32 v50, v2
	v_mov_b32_e32 v51, v2
	v_mov_b32_e32 v52, v2
	v_mov_b32_e32 v53, v2
	v_mov_b32_e32 v54, v2
	v_mov_b32_e32 v55, v2
	v_mov_b32_e32 v56, v2
	v_mov_b32_e32 v57, v2
	v_mov_b32_e32 v10, v2
	v_mov_b32_e32 v11, v2
	v_mov_b32_e32 v12, v2
	v_mov_b32_e32 v13, v2
	v_mov_b32_e32 v14, v2
	v_mov_b32_e32 v15, v2
	v_mov_b32_e32 v16, v2
	v_mov_b32_e32 v17, v2
	v_mov_b32_e32 v26, v2
	v_mov_b32_e32 v27, v2
	v_mov_b32_e32 v28, v2
	v_mov_b32_e32 v29, v2
	v_mov_b32_e32 v30, v2
	v_mov_b32_e32 v31, v2
	v_mov_b32_e32 v32, v2
	v_mov_b32_e32 v33, v2
	v_mov_b32_e32 v42, v2
	v_mov_b32_e32 v43, v2
	v_mov_b32_e32 v44, v2
	v_mov_b32_e32 v45, v2
	v_mov_b32_e32 v46, v2
	v_mov_b32_e32 v47, v2
	v_mov_b32_e32 v48, v2
	v_mov_b32_e32 v49, v2
	v_mov_b32_e32 v58, v2
	v_mov_b32_e32 v59, v2
	v_mov_b32_e32 v60, v2
	v_mov_b32_e32 v61, v2
	v_mov_b32_e32 v62, v2
	v_mov_b32_e32 v63, v2
	v_mov_b32_e32 v64, v2
	v_mov_b32_e32 v65, v2
	v_mov_b32_e32 v66, v2
	v_mov_b32_e32 v67, v2
	v_mov_b32_e32 v68, v2
	v_mov_b32_e32 v69, v2
	v_mov_b32_e32 v70, v2
	v_mov_b32_e32 v71, v2
	v_mov_b32_e32 v72, v2
	v_mov_b32_e32 v73, v2
	v_mov_b32_e32 v82, v2
	v_mov_b32_e32 v83, v2
	v_mov_b32_e32 v84, v2
	v_mov_b32_e32 v85, v2
	v_mov_b32_e32 v94, v2
	v_mov_b32_e32 v95, v2
	v_mov_b32_e32 v96, v2
	v_mov_b32_e32 v97, v2
	v_mov_b32_e32 v132, v2
	v_mov_b32_e32 v133, v2
	v_mov_b32_e32 v134, v2
	v_mov_b32_e32 v135, v2
	v_mov_b32_e32 v136, v2
	v_mov_b32_e32 v137, v2
	v_mov_b32_e32 v138, v2
	v_mov_b32_e32 v139, v2
	v_mov_b32_e32 v148, v2
	v_mov_b32_e32 v149, v2
	v_mov_b32_e32 v150, v2
	v_mov_b32_e32 v151, v2
	v_mov_b32_e32 v152, v2
	v_mov_b32_e32 v153, v2
	v_mov_b32_e32 v154, v2
	v_mov_b32_e32 v155, v2
	v_mov_b32_e32 v74, v2
	v_mov_b32_e32 v75, v2
	v_mov_b32_e32 v76, v2
	v_mov_b32_e32 v77, v2
	v_mov_b32_e32 v78, v2
	v_mov_b32_e32 v79, v2
	v_mov_b32_e32 v80, v2
	v_mov_b32_e32 v81, v2
	v_mov_b32_e32 v120, v2
	v_mov_b32_e32 v121, v2
	v_mov_b32_e32 v122, v2
	v_mov_b32_e32 v123, v2
	v_mov_b32_e32 v128, v2
	v_mov_b32_e32 v129, v2
	v_mov_b32_e32 v130, v2
	v_mov_b32_e32 v131, v2
	v_mov_b32_e32 v140, v2
	v_mov_b32_e32 v141, v2
	v_mov_b32_e32 v142, v2
	v_mov_b32_e32 v143, v2
	v_mov_b32_e32 v144, v2
	v_mov_b32_e32 v145, v2
	v_mov_b32_e32 v146, v2
	v_mov_b32_e32 v147, v2
	v_mov_b32_e32 v156, v2
	v_mov_b32_e32 v157, v2
	v_mov_b32_e32 v158, v2
	v_mov_b32_e32 v159, v2
	v_mov_b32_e32 v160, v2
	v_mov_b32_e32 v161, v2
	v_mov_b32_e32 v162, v2
	v_mov_b32_e32 v163, v2
	s_bitcmp0_b32 s74, 12
	s_cbranch_scc0 .Lmy_sp_g2b
	s_setprio 1

.LBB0_1010:
	s_ashr_i32 s21, s20, 31
	s_lshl_b64 s[4:5], s[20:21], 19
	s_add_u32 s30, s22, s4
	s_addc_u32 s31, s23, s5
	s_and_b64 s[4:5], s[36:37], exec
	s_cselect_b32 s21, s31, s41
	s_cselect_b32 s88, s30, s40
	s_ashr_i32 s15, s14, 31
	s_lshl_b64 s[4:5], s[14:15], 19
	s_add_u32 s38, s18, s4
	s_addc_u32 s39, s27, s5
	s_and_b64 s[4:5], s[36:37], exec
	s_cselect_b32 s15, s39, s57
	s_cselect_b32 s89, s38, s56
	s_add_u32 s40, s40, 0x40080
	s_addc_u32 s41, s41, 0
	s_add_u32 s90, s56, 0x100
	v_mov_b32_e32 v2, 0
	s_addc_u32 s91, s57, 0
	s_mov_b32 s92, -2
	v_mov_b32_e32 v3, v2
	v_mov_b32_e32 v4, v2
	v_mov_b32_e32 v5, v2
	v_mov_b32_e32 v6, v2
	v_mov_b32_e32 v7, v2
	v_mov_b32_e32 v8, v2
	v_mov_b32_e32 v9, v2
	v_mov_b32_e32 v18, v2
	v_mov_b32_e32 v19, v2
	v_mov_b32_e32 v20, v2
	v_mov_b32_e32 v21, v2
	v_mov_b32_e32 v22, v2
	v_mov_b32_e32 v23, v2
	v_mov_b32_e32 v24, v2
	v_mov_b32_e32 v25, v2
	v_mov_b32_e32 v34, v2
	v_mov_b32_e32 v35, v2
	v_mov_b32_e32 v36, v2
	v_mov_b32_e32 v37, v2
	v_mov_b32_e32 v38, v2
	v_mov_b32_e32 v39, v2
	v_mov_b32_e32 v40, v2
	v_mov_b32_e32 v41, v2
	v_mov_b32_e32 v50, v2
	v_mov_b32_e32 v51, v2
	v_mov_b32_e32 v52, v2
	v_mov_b32_e32 v53, v2
	v_mov_b32_e32 v54, v2
	v_mov_b32_e32 v55, v2
	v_mov_b32_e32 v56, v2
	v_mov_b32_e32 v57, v2
	v_mov_b32_e32 v10, v2
	v_mov_b32_e32 v11, v2
	v_mov_b32_e32 v12, v2
	v_mov_b32_e32 v13, v2
	v_mov_b32_e32 v14, v2
	v_mov_b32_e32 v15, v2
	v_mov_b32_e32 v16, v2
	v_mov_b32_e32 v17, v2
	v_mov_b32_e32 v26, v2
	v_mov_b32_e32 v27, v2
	v_mov_b32_e32 v28, v2
	v_mov_b32_e32 v29, v2
	v_mov_b32_e32 v30, v2
	v_mov_b32_e32 v31, v2
	v_mov_b32_e32 v32, v2
	v_mov_b32_e32 v33, v2
	v_mov_b32_e32 v42, v2
	v_mov_b32_e32 v43, v2
	v_mov_b32_e32 v44, v2
	v_mov_b32_e32 v45, v2
	v_mov_b32_e32 v46, v2
	v_mov_b32_e32 v47, v2
	v_mov_b32_e32 v48, v2
	v_mov_b32_e32 v49, v2
	v_mov_b32_e32 v58, v2
	v_mov_b32_e32 v59, v2
	v_mov_b32_e32 v60, v2
	v_mov_b32_e32 v61, v2
	v_mov_b32_e32 v62, v2
	v_mov_b32_e32 v63, v2
	v_mov_b32_e32 v64, v2
	v_mov_b32_e32 v65, v2
	v_mov_b32_e32 v66, v2
	v_mov_b32_e32 v67, v2
	v_mov_b32_e32 v68, v2
	v_mov_b32_e32 v69, v2
	v_mov_b32_e32 v70, v2
	v_mov_b32_e32 v71, v2
	v_mov_b32_e32 v72, v2
	v_mov_b32_e32 v73, v2
	v_mov_b32_e32 v82, v2
	v_mov_b32_e32 v83, v2
	v_mov_b32_e32 v84, v2
	v_mov_b32_e32 v85, v2
	v_mov_b32_e32 v86, v2
	v_mov_b32_e32 v87, v2
	v_mov_b32_e32 v88, v2
	v_mov_b32_e32 v89, v2
	v_mov_b32_e32 v100, v2
	v_mov_b32_e32 v101, v2
	v_mov_b32_e32 v102, v2
	v_mov_b32_e32 v103, v2
	v_mov_b32_e32 v104, v2
	v_mov_b32_e32 v105, v2
	v_mov_b32_e32 v106, v2
	v_mov_b32_e32 v107, v2
	v_mov_b32_e32 v116, v2
	v_mov_b32_e32 v117, v2
	v_mov_b32_e32 v118, v2
	v_mov_b32_e32 v119, v2
	v_mov_b32_e32 v120, v2
	v_mov_b32_e32 v121, v2
	v_mov_b32_e32 v122, v2
	v_mov_b32_e32 v123, v2
	v_mov_b32_e32 v74, v2
	v_mov_b32_e32 v75, v2
	v_mov_b32_e32 v76, v2
	v_mov_b32_e32 v77, v2
	v_mov_b32_e32 v78, v2
	v_mov_b32_e32 v79, v2
	v_mov_b32_e32 v80, v2
	v_mov_b32_e32 v81, v2
	v_mov_b32_e32 v90, v2
	v_mov_b32_e32 v91, v2
	v_mov_b32_e32 v92, v2
	v_mov_b32_e32 v93, v2
	v_mov_b32_e32 v94, v2
	v_mov_b32_e32 v95, v2
	v_mov_b32_e32 v96, v2
	v_mov_b32_e32 v97, v2
	v_mov_b32_e32 v108, v2
	v_mov_b32_e32 v109, v2
	v_mov_b32_e32 v110, v2
	v_mov_b32_e32 v111, v2
	v_mov_b32_e32 v112, v2
	v_mov_b32_e32 v113, v2
	v_mov_b32_e32 v114, v2
	v_mov_b32_e32 v115, v2
	v_mov_b32_e32 v124, v2
	v_mov_b32_e32 v125, v2
	v_mov_b32_e32 v126, v2
	v_mov_b32_e32 v127, v2
	v_mov_b32_e32 v128, v2
	v_mov_b32_e32 v129, v2
	v_mov_b32_e32 v130, v2
	v_mov_b32_e32 v131, v2
	s_bitcmp0_b32 s70, 12
	s_cbranch_scc0 .Lmy_sp_g3
	s_setprio 1

.LBB0_1115:
	s_ashr_i32 s27, s26, 31
	s_lshl_b64 s[4:5], s[26:27], 21
	s_add_u32 s40, s24, s4
	s_addc_u32 s41, s25, s5
	s_and_b64 s[4:5], s[30:31], exec
	s_cselect_b32 s18, s41, s75
	s_cselect_b32 s21, s40, s74
	s_ashr_i32 s69, s68, 31
	s_lshl_b64 s[4:5], s[68:69], 21
	s_add_u32 s56, s77, s4
	s_addc_u32 s57, s88, s5
	s_and_b64 s[4:5], s[30:31], exec
	s_cselect_b32 s27, s57, s79
	s_cselect_b32 s69, s56, s78
	s_add_u32 s74, s74, 0x100080
	s_addc_u32 s75, s75, 0
	s_add_u32 s71, s78, 0x100
	v_mov_b32_e32 v2, 0
	s_addc_u32 s94, s79, 0
	s_mov_b32 s95, -2
	s_waitcnt lgkmcnt(0)
	v_mov_b32_e32 v3, v2
	v_mov_b32_e32 v4, v2
	v_mov_b32_e32 v5, v2
	v_mov_b32_e32 v6, v2
	v_mov_b32_e32 v7, v2
	v_mov_b32_e32 v8, v2
	v_mov_b32_e32 v9, v2
	v_mov_b32_e32 v18, v2
	v_mov_b32_e32 v19, v2
	v_mov_b32_e32 v20, v2
	v_mov_b32_e32 v21, v2
	v_mov_b32_e32 v22, v2
	v_mov_b32_e32 v23, v2
	v_mov_b32_e32 v24, v2
	v_mov_b32_e32 v25, v2
	v_mov_b32_e32 v34, v2
	v_mov_b32_e32 v35, v2
	v_mov_b32_e32 v36, v2
	v_mov_b32_e32 v37, v2
	v_mov_b32_e32 v38, v2
	v_mov_b32_e32 v39, v2
	v_mov_b32_e32 v40, v2
	v_mov_b32_e32 v41, v2
	v_mov_b32_e32 v50, v2
	v_mov_b32_e32 v51, v2
	v_mov_b32_e32 v52, v2
	v_mov_b32_e32 v53, v2
	v_mov_b32_e32 v54, v2
	v_mov_b32_e32 v55, v2
	v_mov_b32_e32 v56, v2
	v_mov_b32_e32 v57, v2
	v_mov_b32_e32 v10, v2
	v_mov_b32_e32 v11, v2
	v_mov_b32_e32 v12, v2
	v_mov_b32_e32 v13, v2
	v_mov_b32_e32 v14, v2
	v_mov_b32_e32 v15, v2
	v_mov_b32_e32 v16, v2
	v_mov_b32_e32 v17, v2
	v_mov_b32_e32 v26, v2
	v_mov_b32_e32 v27, v2
	v_mov_b32_e32 v28, v2
	v_mov_b32_e32 v29, v2
	v_mov_b32_e32 v30, v2
	v_mov_b32_e32 v31, v2
	v_mov_b32_e32 v32, v2
	v_mov_b32_e32 v33, v2
	v_mov_b32_e32 v42, v2
	v_mov_b32_e32 v43, v2
	v_mov_b32_e32 v44, v2
	v_mov_b32_e32 v45, v2
	v_mov_b32_e32 v46, v2
	v_mov_b32_e32 v47, v2
	v_mov_b32_e32 v48, v2
	v_mov_b32_e32 v49, v2
	v_mov_b32_e32 v58, v2
	v_mov_b32_e32 v59, v2
	v_mov_b32_e32 v60, v2
	v_mov_b32_e32 v61, v2
	v_mov_b32_e32 v62, v2
	v_mov_b32_e32 v63, v2
	v_mov_b32_e32 v64, v2
	v_mov_b32_e32 v65, v2
	v_mov_b32_e32 v66, v2
	v_mov_b32_e32 v67, v2
	v_mov_b32_e32 v68, v2
	v_mov_b32_e32 v69, v2
	v_mov_b32_e32 v70, v2
	v_mov_b32_e32 v71, v2
	v_mov_b32_e32 v72, v2
	v_mov_b32_e32 v73, v2
	v_mov_b32_e32 v82, v2
	v_mov_b32_e32 v83, v2
	v_mov_b32_e32 v84, v2
	v_mov_b32_e32 v85, v2
	v_mov_b32_e32 v86, v2
	v_mov_b32_e32 v87, v2
	v_mov_b32_e32 v88, v2
	v_mov_b32_e32 v89, v2
	v_mov_b32_e32 v100, v2
	v_mov_b32_e32 v101, v2
	v_mov_b32_e32 v102, v2
	v_mov_b32_e32 v103, v2
	v_mov_b32_e32 v104, v2
	v_mov_b32_e32 v105, v2
	v_mov_b32_e32 v106, v2
	v_mov_b32_e32 v107, v2
	v_mov_b32_e32 v132, v2
	v_mov_b32_e32 v133, v2
	v_mov_b32_e32 v134, v2
	v_mov_b32_e32 v135, v2
	v_mov_b32_e32 v136, v2
	v_mov_b32_e32 v137, v2
	v_mov_b32_e32 v138, v2
	v_mov_b32_e32 v139, v2
	v_mov_b32_e32 v74, v2
	v_mov_b32_e32 v75, v2
	v_mov_b32_e32 v76, v2
	v_mov_b32_e32 v77, v2
	v_mov_b32_e32 v78, v2
	v_mov_b32_e32 v79, v2
	v_mov_b32_e32 v80, v2
	v_mov_b32_e32 v81, v2
	v_mov_b32_e32 v90, v2
	v_mov_b32_e32 v91, v2
	v_mov_b32_e32 v92, v2
	v_mov_b32_e32 v93, v2
	v_mov_b32_e32 v94, v2
	v_mov_b32_e32 v95, v2
	v_mov_b32_e32 v96, v2
	v_mov_b32_e32 v97, v2
	v_mov_b32_e32 v108, v2
	v_mov_b32_e32 v109, v2
	v_mov_b32_e32 v110, v2
	v_mov_b32_e32 v111, v2
	v_mov_b32_e32 v120, v2
	v_mov_b32_e32 v121, v2
	v_mov_b32_e32 v122, v2
	v_mov_b32_e32 v123, v2
	v_mov_b32_e32 v140, v2
	v_mov_b32_e32 v141, v2
	v_mov_b32_e32 v142, v2
	v_mov_b32_e32 v143, v2
	v_mov_b32_e32 v144, v2
	v_mov_b32_e32 v145, v2
	v_mov_b32_e32 v146, v2
	v_mov_b32_e32 v147, v2
	s_bitcmp0_b32 s91, 12
	s_cbranch_scc0 .Lmy_sp_g4a
	s_setprio 1

.LBB0_1171:
	s_ashr_i32 s27, s26, 31
	s_lshl_b64 s[4:5], s[26:27], 21
	s_add_u32 s40, s24, s4
	s_addc_u32 s41, s25, s5
	s_and_b64 s[4:5], s[30:31], exec
	s_cselect_b32 s18, s41, s71
	s_cselect_b32 s27, s40, s70
	s_ashr_i32 s15, s14, 31
	s_lshl_b64 s[4:5], s[14:15], 21
	s_add_u32 s20, s77, s4
	s_addc_u32 s21, s88, s5
	s_and_b64 s[4:5], s[30:31], exec
	s_cselect_b32 s15, s21, s75
	s_cselect_b32 s57, s20, s74
	s_add_u32 s70, s70, 0x100080
	s_addc_u32 s71, s71, 0
	s_add_u32 s69, s74, 0x100
	v_mov_b32_e32 v2, 0
	s_addc_u32 s94, s75, 0
	s_mov_b32 s95, -2
	s_waitcnt lgkmcnt(0)
	v_mov_b32_e32 v3, v2
	v_mov_b32_e32 v4, v2
	v_mov_b32_e32 v5, v2
	v_mov_b32_e32 v6, v2
	v_mov_b32_e32 v7, v2
	v_mov_b32_e32 v8, v2
	v_mov_b32_e32 v9, v2
	v_mov_b32_e32 v18, v2
	v_mov_b32_e32 v19, v2
	v_mov_b32_e32 v20, v2
	v_mov_b32_e32 v21, v2
	v_mov_b32_e32 v22, v2
	v_mov_b32_e32 v23, v2
	v_mov_b32_e32 v24, v2
	v_mov_b32_e32 v25, v2
	v_mov_b32_e32 v34, v2
	v_mov_b32_e32 v35, v2
	v_mov_b32_e32 v36, v2
	v_mov_b32_e32 v37, v2
	v_mov_b32_e32 v38, v2
	v_mov_b32_e32 v39, v2
	v_mov_b32_e32 v40, v2
	v_mov_b32_e32 v41, v2
	v_mov_b32_e32 v50, v2
	v_mov_b32_e32 v51, v2
	v_mov_b32_e32 v52, v2
	v_mov_b32_e32 v53, v2
	v_mov_b32_e32 v54, v2
	v_mov_b32_e32 v55, v2
	v_mov_b32_e32 v56, v2
	v_mov_b32_e32 v57, v2
	v_mov_b32_e32 v10, v2
	v_mov_b32_e32 v11, v2
	v_mov_b32_e32 v12, v2
	v_mov_b32_e32 v13, v2
	v_mov_b32_e32 v14, v2
	v_mov_b32_e32 v15, v2
	v_mov_b32_e32 v16, v2
	v_mov_b32_e32 v17, v2
	v_mov_b32_e32 v26, v2
	v_mov_b32_e32 v27, v2
	v_mov_b32_e32 v28, v2
	v_mov_b32_e32 v29, v2
	v_mov_b32_e32 v30, v2
	v_mov_b32_e32 v31, v2
	v_mov_b32_e32 v32, v2
	v_mov_b32_e32 v33, v2
	v_mov_b32_e32 v42, v2
	v_mov_b32_e32 v43, v2
	v_mov_b32_e32 v44, v2
	v_mov_b32_e32 v45, v2
	v_mov_b32_e32 v46, v2
	v_mov_b32_e32 v47, v2
	v_mov_b32_e32 v48, v2
	v_mov_b32_e32 v49, v2
	v_mov_b32_e32 v58, v2
	v_mov_b32_e32 v59, v2
	v_mov_b32_e32 v60, v2
	v_mov_b32_e32 v61, v2
	v_mov_b32_e32 v62, v2
	v_mov_b32_e32 v63, v2
	v_mov_b32_e32 v64, v2
	v_mov_b32_e32 v65, v2
	v_mov_b32_e32 v66, v2
	v_mov_b32_e32 v67, v2
	v_mov_b32_e32 v68, v2
	v_mov_b32_e32 v69, v2
	v_mov_b32_e32 v70, v2
	v_mov_b32_e32 v71, v2
	v_mov_b32_e32 v72, v2
	v_mov_b32_e32 v73, v2
	v_mov_b32_e32 v82, v2
	v_mov_b32_e32 v83, v2
	v_mov_b32_e32 v84, v2
	v_mov_b32_e32 v85, v2
	v_mov_b32_e32 v86, v2
	v_mov_b32_e32 v87, v2
	v_mov_b32_e32 v88, v2
	v_mov_b32_e32 v89, v2
	v_mov_b32_e32 v132, v2
	v_mov_b32_e32 v133, v2
	v_mov_b32_e32 v134, v2
	v_mov_b32_e32 v135, v2
	v_mov_b32_e32 v136, v2
	v_mov_b32_e32 v137, v2
	v_mov_b32_e32 v138, v2
	v_mov_b32_e32 v139, v2
	v_mov_b32_e32 v148, v2
	v_mov_b32_e32 v149, v2
	v_mov_b32_e32 v150, v2
	v_mov_b32_e32 v151, v2
	v_mov_b32_e32 v152, v2
	v_mov_b32_e32 v153, v2
	v_mov_b32_e32 v154, v2
	v_mov_b32_e32 v155, v2
	v_mov_b32_e32 v74, v2
	v_mov_b32_e32 v75, v2
	v_mov_b32_e32 v76, v2
	v_mov_b32_e32 v77, v2
	v_mov_b32_e32 v78, v2
	v_mov_b32_e32 v79, v2
	v_mov_b32_e32 v80, v2
	v_mov_b32_e32 v81, v2
	v_mov_b32_e32 v116, v2
	v_mov_b32_e32 v117, v2
	v_mov_b32_e32 v118, v2
	v_mov_b32_e32 v119, v2
	v_mov_b32_e32 v124, v2
	v_mov_b32_e32 v125, v2
	v_mov_b32_e32 v126, v2
	v_mov_b32_e32 v127, v2
	v_mov_b32_e32 v140, v2
	v_mov_b32_e32 v141, v2
	v_mov_b32_e32 v142, v2
	v_mov_b32_e32 v143, v2
	v_mov_b32_e32 v144, v2
	v_mov_b32_e32 v145, v2
	v_mov_b32_e32 v146, v2
	v_mov_b32_e32 v147, v2
	v_mov_b32_e32 v156, v2
	v_mov_b32_e32 v157, v2
	v_mov_b32_e32 v158, v2
	v_mov_b32_e32 v159, v2
	v_mov_b32_e32 v160, v2
	v_mov_b32_e32 v161, v2
	v_mov_b32_e32 v162, v2
	v_mov_b32_e32 v163, v2
	s_bitcmp0_b32 s91, 12
	s_cbranch_scc0 .Lmy_sp_g4b
	s_setprio 1
